# counted-wait repair: removed hipcc's loop-carried WAW vmcnt waits inside skinny_ks load-issue section (sample-row split-K GEMM chunks were serialised), on top of stack7
# baseline (speedup 1.0000x reference)
.LBB0_213:
	s_ashr_i32 s6, s22, 31
	s_lshr_b32 s6, s6, 26
	s_add_i32 s6, s22, s6
	s_ashr_i32 s16, s6, 6
	s_mul_i32 s6, s16, 22
	s_add_i32 s6, s6, s18
	s_lshl_b32 s6, s6, 6
	s_ashr_i32 s7, s6, 31
	s_lshl_b64 s[6:7], s[6:7], 1
	v_lshl_add_u64 v[102:103], v[118:119], 0, s[6:7]
	v_lshl_add_u64 v[4:5], v[120:121], 0, s[6:7]
	s_mul_i32 s6, s16, 0xff500000
	v_add_u32_e32 v104, s6, v126
	v_ashrrev_i32_e32 v105, 31, v104
	s_and_b64 vcc, exec, s[4:5]
	v_lshl_add_u64 v[4:5], v[104:105], 1, v[4:5]
	s_cbranch_vccnz .LBB0_215
	v_add_co_u32_e32 v46, vcc, 0x2c000, v102
	global_load_dwordx4 v[34:37], v[102:103], off
	global_load_dwordx4 v[30:33], v[102:103], off offset:64
	v_addc_co_u32_e32 v47, vcc, 0, v103, vcc
	global_load_dwordx4 v[50:53], v[46:47], off
	s_nop 0
	global_load_dwordx4 v[46:49], v[46:47], off offset:64
	s_nop 0
	global_load_dwordx4 v[82:85], v[4:5], off
	global_load_dwordx4 v[78:81], v[4:5], off offset:64
	v_add_co_u32_e32 v94, vcc, 0x2c000, v4
	s_nop 1
	v_addc_co_u32_e32 v95, vcc, 0, v5, vcc
	global_load_dwordx4 v[98:101], v[94:95], off
	s_nop 0
	global_load_dwordx4 v[94:97], v[94:95], off offset:64
.LBB0_215:
	v_cndmask_b32_e64 v3, 0, 1, s[12:13]
	v_cmp_ne_u32_e64 s[6:7], 1, v3
	s_andn2_b64 vcc, exec, s[12:13]
	s_cbranch_vccnz .LBB0_222
	v_add_co_u32_e32 v38, vcc, 0x2c000, v102
	global_load_dwordx4 v[18:21], v[102:103], off offset:128
	global_load_dwordx4 v[14:17], v[102:103], off offset:192
	v_addc_co_u32_e32 v39, vcc, 0, v103, vcc
	global_load_dwordx4 v[42:45], v[38:39], off offset:128
	s_nop 0
	global_load_dwordx4 v[38:41], v[38:39], off offset:192
	s_nop 0
	global_load_dwordx4 v[66:69], v[4:5], off offset:128
	global_load_dwordx4 v[62:65], v[4:5], off offset:192
	v_add_co_u32_e32 v86, vcc, 0x2c000, v4
	s_nop 1
	v_addc_co_u32_e32 v87, vcc, 0, v5, vcc
	global_load_dwordx4 v[90:93], v[86:87], off offset:128
	s_nop 0
	global_load_dwordx4 v[86:89], v[86:87], off offset:192
	v_cndmask_b32_e64 v3, 0, 1, s[14:15]
	v_cmp_ne_u32_e64 s[8:9], 1, v3
	s_andn2_b64 vcc, exec, s[14:15]
	s_cbranch_vccz .LBB0_223

.LBB0_223:
	v_add_co_u32_e32 v22, vcc, 0x2c000, v102
	global_load_dwordx4 v[10:13], v[102:103], off offset:256
	global_load_dwordx4 v[6:9], v[102:103], off offset:320
	v_addc_co_u32_e32 v23, vcc, 0, v103, vcc
	global_load_dwordx4 v[26:29], v[22:23], off offset:256
	s_nop 0
	global_load_dwordx4 v[22:25], v[22:23], off offset:320
	s_nop 0
	global_load_dwordx4 v[58:61], v[4:5], off offset:256
	global_load_dwordx4 v[54:57], v[4:5], off offset:320
	v_add_co_u32_e32 v4, vcc, 0x2c000, v4
	s_nop 1
	v_addc_co_u32_e32 v5, vcc, 0, v5, vcc
	global_load_dwordx4 v[74:77], v[4:5], off offset:256
	global_load_dwordx4 v[70:73], v[4:5], off offset:320
	s_and_b64 vcc, exec, s[4:5]
	s_cbranch_vccz .LBB0_218

.LBB0_1671:
	s_ashr_i32 s6, s24, 31
	s_lshr_b32 s6, s6, 26
	s_add_i32 s6, s24, s6
	s_ashr_i32 s16, s6, 6
	s_mul_i32 s6, s16, 22
	s_add_i32 s6, s6, s20
	s_lshl_b32 s6, s6, 6
	s_ashr_i32 s7, s6, 31
	s_lshl_b64 s[6:7], s[6:7], 1
	v_lshl_add_u64 v[102:103], v[118:119], 0, s[6:7]
	v_lshl_add_u64 v[4:5], v[120:121], 0, s[6:7]
	s_mul_i32 s6, s16, 0xff500000
	v_add_u32_e32 v104, s6, v126
	v_ashrrev_i32_e32 v105, 31, v104
	s_and_b64 vcc, exec, s[4:5]
	v_lshl_add_u64 v[4:5], v[104:105], 1, v[4:5]
	s_cbranch_vccnz .LBB0_1673
	v_add_co_u32_e32 v46, vcc, 0x2c000, v102
	global_load_dwordx4 v[34:37], v[102:103], off
	global_load_dwordx4 v[30:33], v[102:103], off offset:64
	v_addc_co_u32_e32 v47, vcc, 0, v103, vcc
	global_load_dwordx4 v[50:53], v[46:47], off
	s_nop 0
	global_load_dwordx4 v[46:49], v[46:47], off offset:64
	s_nop 0
	global_load_dwordx4 v[82:85], v[4:5], off
	global_load_dwordx4 v[78:81], v[4:5], off offset:64
	v_add_co_u32_e32 v94, vcc, 0x2c000, v4
	s_nop 1
	v_addc_co_u32_e32 v95, vcc, 0, v5, vcc
	global_load_dwordx4 v[98:101], v[94:95], off
	s_nop 0
	global_load_dwordx4 v[94:97], v[94:95], off offset:64

.LBB0_2546:
	s_ashr_i32 s4, s22, 31
	s_lshr_b32 s4, s4, 26
	s_add_i32 s4, s22, s4
	s_ashr_i32 s14, s4, 6
	s_mul_i32 s4, s14, 22
	s_add_i32 s4, s4, s16
	s_lshl_b32 s4, s4, 6
	s_ashr_i32 s5, s4, 31
	s_lshl_b64 s[4:5], s[4:5], 1
	v_lshl_add_u64 v[102:103], v[118:119], 0, s[4:5]
	v_lshl_add_u64 v[4:5], v[120:121], 0, s[4:5]
	s_mul_i32 s4, s14, 0xff500000
	v_add_u32_e32 v104, s4, v126
	v_ashrrev_i32_e32 v105, 31, v104
	s_and_b64 vcc, exec, s[0:1]
	v_lshl_add_u64 v[4:5], v[104:105], 1, v[4:5]
	s_cbranch_vccnz .LBB0_2548
	v_add_co_u32_e32 v46, vcc, 0x2c000, v102
	global_load_dwordx4 v[34:37], v[102:103], off
	global_load_dwordx4 v[30:33], v[102:103], off offset:64
	v_addc_co_u32_e32 v47, vcc, 0, v103, vcc
	global_load_dwordx4 v[50:53], v[46:47], off
	s_nop 0
	global_load_dwordx4 v[46:49], v[46:47], off offset:64
	s_nop 0
	global_load_dwordx4 v[82:85], v[4:5], off
	global_load_dwordx4 v[78:81], v[4:5], off offset:64
	v_add_co_u32_e32 v94, vcc, 0x2c000, v4
	s_nop 1
	v_addc_co_u32_e32 v95, vcc, 0, v5, vcc
	global_load_dwordx4 v[98:101], v[94:95], off
	s_nop 0
	global_load_dwordx4 v[94:97], v[94:95], off offset:64
.LBB0_2548:
	v_cndmask_b32_e64 v3, 0, 1, s[10:11]
	v_cmp_ne_u32_e64 s[4:5], 1, v3
	s_andn2_b64 vcc, exec, s[10:11]
	s_cbranch_vccnz .LBB0_2555
	v_add_co_u32_e32 v38, vcc, 0x2c000, v102
	global_load_dwordx4 v[18:21], v[102:103], off offset:128
	global_load_dwordx4 v[14:17], v[102:103], off offset:192
	v_addc_co_u32_e32 v39, vcc, 0, v103, vcc
	global_load_dwordx4 v[42:45], v[38:39], off offset:128
	s_nop 0
	global_load_dwordx4 v[38:41], v[38:39], off offset:192
	s_nop 0
	global_load_dwordx4 v[66:69], v[4:5], off offset:128
	global_load_dwordx4 v[62:65], v[4:5], off offset:192
	v_add_co_u32_e32 v86, vcc, 0x2c000, v4
	s_nop 1
	v_addc_co_u32_e32 v87, vcc, 0, v5, vcc
	global_load_dwordx4 v[90:93], v[86:87], off offset:128
	s_nop 0
	global_load_dwordx4 v[86:89], v[86:87], off offset:192
	v_cndmask_b32_e64 v3, 0, 1, s[12:13]
	v_cmp_ne_u32_e64 s[6:7], 1, v3
	s_andn2_b64 vcc, exec, s[12:13]
	s_cbranch_vccz .LBB0_2556

.LBB0_2556:
	v_add_co_u32_e32 v22, vcc, 0x2c000, v102
	global_load_dwordx4 v[10:13], v[102:103], off offset:256
	global_load_dwordx4 v[6:9], v[102:103], off offset:320
	v_addc_co_u32_e32 v23, vcc, 0, v103, vcc
	global_load_dwordx4 v[26:29], v[22:23], off offset:256
	s_nop 0
	global_load_dwordx4 v[22:25], v[22:23], off offset:320
	s_nop 0
	global_load_dwordx4 v[58:61], v[4:5], off offset:256
	global_load_dwordx4 v[54:57], v[4:5], off offset:320
	v_add_co_u32_e32 v4, vcc, 0x2c000, v4
	s_nop 1
	v_addc_co_u32_e32 v5, vcc, 0, v5, vcc
	global_load_dwordx4 v[74:77], v[4:5], off offset:256
	global_load_dwordx4 v[70:73], v[4:5], off offset:320
	s_and_b64 vcc, exec, s[0:1]
	s_cbranch_vccz .LBB0_2551

.LBB0_2986:
	s_ashr_i32 s4, s21, 31
	s_lshr_b32 s4, s4, 25
	s_add_i32 s4, s21, s4
	s_ashr_i32 s14, s4, 7
	s_lshl_b32 s4, s14, 10
	s_add_i32 s4, s4, s16
	s_ashr_i32 s5, s4, 31
	s_lshl_b64 s[4:5], s[4:5], 1
	s_lshl_b32 s15, s14, 12
	v_lshl_add_u64 v[4:5], v[118:119], 0, s[4:5]
	v_lshl_add_u64 v[102:103], v[120:121], 0, s[4:5]
	s_sub_i32 s4, s17, s15
	v_add_u32_e32 v104, s4, v167
	v_ashrrev_i32_e32 v105, 31, v104
	v_lshlrev_b64 v[104:105], 12, v[104:105]
	s_and_b64 vcc, exec, s[0:1]
	v_lshl_add_u64 v[102:103], v[102:103], 0, v[104:105]
	s_cbranch_vccnz .LBB0_2988
	v_add_co_u32_e32 v46, vcc, 0x10000, v4
	global_load_dwordx4 v[34:37], v[4:5], off
	global_load_dwordx4 v[30:33], v[4:5], off offset:64
	v_addc_co_u32_e32 v47, vcc, 0, v5, vcc
	global_load_dwordx4 v[50:53], v[46:47], off
	s_nop 0
	global_load_dwordx4 v[46:49], v[46:47], off offset:64
	s_nop 0
	global_load_dwordx4 v[82:85], v[102:103], off
	global_load_dwordx4 v[78:81], v[102:103], off offset:64
	v_add_co_u32_e32 v94, vcc, 0x10000, v102
	s_nop 1
	v_addc_co_u32_e32 v95, vcc, 0, v103, vcc
	global_load_dwordx4 v[98:101], v[94:95], off
	s_nop 0
	global_load_dwordx4 v[94:97], v[94:95], off offset:64
.LBB0_2988:
	v_cndmask_b32_e64 v3, 0, 1, s[10:11]
	v_cmp_ne_u32_e64 s[4:5], 1, v3
	s_andn2_b64 vcc, exec, s[10:11]
	s_cbranch_vccnz .LBB0_2995
	v_add_co_u32_e32 v38, vcc, 0x10000, v4
	global_load_dwordx4 v[18:21], v[4:5], off offset:128
	global_load_dwordx4 v[14:17], v[4:5], off offset:192
	v_addc_co_u32_e32 v39, vcc, 0, v5, vcc
	global_load_dwordx4 v[42:45], v[38:39], off offset:128
	s_nop 0
	global_load_dwordx4 v[38:41], v[38:39], off offset:192
	s_nop 0
	global_load_dwordx4 v[66:69], v[102:103], off offset:128
	global_load_dwordx4 v[62:65], v[102:103], off offset:192
	v_add_co_u32_e32 v86, vcc, 0x10000, v102
	s_nop 1
	v_addc_co_u32_e32 v87, vcc, 0, v103, vcc
	global_load_dwordx4 v[90:93], v[86:87], off offset:128
	s_nop 0
	global_load_dwordx4 v[86:89], v[86:87], off offset:192
	v_cndmask_b32_e64 v3, 0, 1, s[12:13]
	v_cmp_ne_u32_e64 s[6:7], 1, v3
	s_andn2_b64 vcc, exec, s[12:13]
	s_cbranch_vccz .LBB0_2996

.LBB0_3463:
	s_ashr_i32 s4, s19, 31
	s_lshr_b32 s4, s4, 26
	s_add_i32 s4, s19, s4
	s_ashr_i32 s14, s4, 6
	s_mul_i32 s4, s14, 22
	s_add_i32 s4, s4, s3
	s_lshl_b32 s4, s4, 6
	s_ashr_i32 s5, s4, 31
	s_lshl_b64 s[4:5], s[4:5], 1
	v_lshl_add_u64 v[102:103], v[118:119], 0, s[4:5]
	v_lshl_add_u64 v[4:5], v[120:121], 0, s[4:5]
	s_mul_i32 s4, s14, 0xff500000
	v_add_u32_e32 v104, s4, v126
	v_ashrrev_i32_e32 v105, 31, v104
	s_and_b64 vcc, exec, s[0:1]
	v_lshl_add_u64 v[4:5], v[104:105], 1, v[4:5]
	s_cbranch_vccnz .LBB0_3465
	v_add_co_u32_e32 v94, vcc, 0x2c000, v102
	global_load_dwordx4 v[34:37], v[102:103], off
	global_load_dwordx4 v[30:33], v[102:103], off offset:64
	v_addc_co_u32_e32 v95, vcc, 0, v103, vcc
	global_load_dwordx4 v[50:53], v[94:95], off
	global_load_dwordx4 v[46:49], v[94:95], off offset:64
	global_load_dwordx4 v[82:85], v[4:5], off
	global_load_dwordx4 v[78:81], v[4:5], off offset:64
	v_add_co_u32_e32 v104, vcc, 0x2c000, v4
	s_nop 1
	v_addc_co_u32_e32 v105, vcc, 0, v5, vcc
	global_load_dwordx4 v[98:101], v[104:105], off
	global_load_dwordx4 v[94:97], v[104:105], off offset:64
.LBB0_3465:
	v_cndmask_b32_e64 v3, 0, 1, s[10:11]
	v_cmp_ne_u32_e64 s[4:5], 1, v3
	s_andn2_b64 vcc, exec, s[10:11]
	s_cbranch_vccnz .LBB0_3472
	v_add_co_u32_e32 v86, vcc, 0x2c000, v102
	global_load_dwordx4 v[18:21], v[102:103], off offset:128
	global_load_dwordx4 v[14:17], v[102:103], off offset:192
	v_addc_co_u32_e32 v87, vcc, 0, v103, vcc
	global_load_dwordx4 v[42:45], v[86:87], off offset:128
	global_load_dwordx4 v[38:41], v[86:87], off offset:192
	global_load_dwordx4 v[66:69], v[4:5], off offset:128
	global_load_dwordx4 v[62:65], v[4:5], off offset:192
	v_add_co_u32_e32 v104, vcc, 0x2c000, v4
	s_nop 1
	v_addc_co_u32_e32 v105, vcc, 0, v5, vcc
	global_load_dwordx4 v[90:93], v[104:105], off offset:128
	global_load_dwordx4 v[86:89], v[104:105], off offset:192
	v_cndmask_b32_e64 v3, 0, 1, s[12:13]
	v_cmp_ne_u32_e64 s[6:7], 1, v3
	s_andn2_b64 vcc, exec, s[12:13]
	s_cbranch_vccz .LBB0_3473

.LBB0_3473:
	v_add_co_u32_e32 v70, vcc, 0x2c000, v102
	global_load_dwordx4 v[10:13], v[102:103], off offset:256
	global_load_dwordx4 v[6:9], v[102:103], off offset:320
	v_addc_co_u32_e32 v71, vcc, 0, v103, vcc
	global_load_dwordx4 v[26:29], v[70:71], off offset:256
	global_load_dwordx4 v[22:25], v[70:71], off offset:320
	global_load_dwordx4 v[58:61], v[4:5], off offset:256
	global_load_dwordx4 v[54:57], v[4:5], off offset:320
	v_add_co_u32_e32 v4, vcc, 0x2c000, v4
	s_nop 1
	v_addc_co_u32_e32 v5, vcc, 0, v5, vcc
	global_load_dwordx4 v[74:77], v[4:5], off offset:256
	global_load_dwordx4 v[70:73], v[4:5], off offset:320
	s_and_b64 vcc, exec, s[0:1]
	s_cbranch_vccz .LBB0_3468
